# all split-K residual pieces via slabs (no float atomics left): token-shift phase reads the last-tile rows from a per-wave scratch copy
# speedup vs baseline: 1.2634x; 1.0051x over previous
.LBB0_3018:
	v_readlane_b32 s12, v252, 30
	v_readlane_b32 s13, v252, 31
	v_mov_b32_e32 v0, v226
	s_andn2_b64 vcc, exec, s[12:13]
	s_mov_b32 s26, 0xb606000
	s_cbranch_vccnz .LBB0_3017
	v_readlane_b32 s14, v250, 6
	s_cmp_gt_u32 s14, 0xff
	s_cbranch_scc1 .Lslab_skip_a
	v_and_b32_e32 v2, 63, v226
	v_lshlrev_b32_e32 v2, 4, v2
	v_lshl_add_u32 v60, s14, 13, v2
	v_mov_b32_e32 v61, 0
	v_lshl_add_u32 v2, s14, 12, v2
	v_mov_b32_e32 v3, 0
	v_readlane_b32 s18, v254, 55
	s_cmp_eq_u32 s18, 1
	s_cbranch_scc1 .Lslab_a_l1
	v_readlane_b32 s14, v250, 15
	v_readlane_b32 s18, v250, 16
	s_add_u32 s12, s14, 0xb506000
	s_addc_u32 s13, s18, 0
	v_lshl_add_u64 v[4:5], s[12:13], 0, v[2:3]
	global_load_dwordx4 v[8:11], v[4:5], off sc1
	global_load_dwordx4 v[12:15], v[4:5], off offset:1024 sc1
	global_load_dwordx4 v[16:19], v[4:5], off offset:2048 sc1
	global_load_dwordx4 v[20:23], v[4:5], off offset:3072 sc1
	v_readlane_b32 s14, v250, 15
	v_readlane_b32 s18, v250, 16
	s_add_u32 s12, s14, 0x284e6000
	s_addc_u32 s13, s18, 0
	global_load_dword v6, v3, s[12:13] sc1
	v_readlane_b32 s14, v250, 15
	v_readlane_b32 s18, v250, 16
	s_add_u32 s12, s14, 0x274e6000
	s_addc_u32 s13, s18, 0
	v_lshl_add_u64 v[24:25], s[12:13], 0, v[2:3]
	s_mov_b64 s[12:13], 0x100000
	v_lshl_add_u64 v[26:27], v[24:25], 0, s[12:13]
	s_mov_b64 s[12:13], 0x200000
	s_waitcnt vmcnt(0)
	v_readfirstlane_b32 s18, v6
	s_lshr_b32 s18, s18, 1
.Lslab_loop_an:
	global_load_dwordx4 v[28:31], v[24:25], off
	global_load_dwordx4 v[32:35], v[24:25], off offset:1024
	global_load_dwordx4 v[36:39], v[24:25], off offset:2048
	global_load_dwordx4 v[40:43], v[24:25], off offset:3072
	global_load_dwordx4 v[44:47], v[26:27], off
	global_load_dwordx4 v[48:51], v[26:27], off offset:1024
	global_load_dwordx4 v[52:55], v[26:27], off offset:2048
	global_load_dwordx4 v[56:59], v[26:27], off offset:3072
	v_lshl_add_u64 v[24:25], v[24:25], 0, s[12:13]
	v_lshl_add_u64 v[26:27], v[26:27], 0, s[12:13]
	s_waitcnt vmcnt(0)
	v_pk_add_f32 v[8:9], v[8:9], v[28:29]
	v_pk_add_f32 v[10:11], v[10:11], v[30:31]
	v_pk_add_f32 v[12:13], v[12:13], v[32:33]
	v_pk_add_f32 v[14:15], v[14:15], v[34:35]
	v_pk_add_f32 v[16:17], v[16:17], v[36:37]
	v_pk_add_f32 v[18:19], v[18:19], v[38:39]
	v_pk_add_f32 v[20:21], v[20:21], v[40:41]
	v_pk_add_f32 v[22:23], v[22:23], v[42:43]
	v_pk_add_f32 v[8:9], v[8:9], v[44:45]
	v_pk_add_f32 v[10:11], v[10:11], v[46:47]
	v_pk_add_f32 v[12:13], v[12:13], v[48:49]
	v_pk_add_f32 v[14:15], v[14:15], v[50:51]
	v_pk_add_f32 v[16:17], v[16:17], v[52:53]
	v_pk_add_f32 v[18:19], v[18:19], v[54:55]
	v_pk_add_f32 v[20:21], v[20:21], v[56:57]
	v_pk_add_f32 v[22:23], v[22:23], v[58:59]
	s_add_i32 s18, s18, -1
	s_cmp_lg_u32 s18, 0
	s_cbranch_scc1 .Lslab_loop_an
	v_readlane_b32 s14, v250, 15
	v_readlane_b32 s18, v250, 16
	s_add_u32 s12, s14, 0xb506000
	s_addc_u32 s13, s18, 0
	v_lshl_add_u64 v[4:5], s[12:13], 0, v[2:3]
	global_store_dwordx4 v[4:5], v[8:11], off
	global_store_dwordx4 v[4:5], v[12:15], off offset:1024
	global_store_dwordx4 v[4:5], v[16:19], off offset:2048
	global_store_dwordx4 v[4:5], v[20:23], off offset:3072
	s_branch .Lslab_done_a
.Lslab_a_l1:
	v_readlane_b32 s14, v250, 13
	v_readlane_b32 s18, v250, 14
	s_add_u32 s12, s14, 0x1000
	s_addc_u32 s13, s18, 0
	v_lshl_add_u64 v[4:5], s[12:13], 0, v[60:61]
	global_load_dwordx4 v[8:11], v[4:5], off sc1
	global_load_dwordx4 v[12:15], v[4:5], off offset:1024 sc1
	global_load_dwordx4 v[16:19], v[4:5], off offset:2048 sc1
	global_load_dwordx4 v[20:23], v[4:5], off offset:3072 sc1
	v_readlane_b32 s14, v250, 15
	v_readlane_b32 s18, v250, 16
	s_add_u32 s12, s14, 0x284e6000
	s_addc_u32 s13, s18, 0
	global_load_dword v6, v3, s[12:13] sc1
	v_readlane_b32 s14, v250, 15
	v_readlane_b32 s18, v250, 16
	s_add_u32 s12, s14, 0x274e6000
	s_addc_u32 s13, s18, 0
	v_lshl_add_u64 v[24:25], s[12:13], 0, v[2:3]
	s_mov_b64 s[12:13], 0x100000
	v_lshl_add_u64 v[26:27], v[24:25], 0, s[12:13]
	s_mov_b64 s[12:13], 0x200000
	s_waitcnt vmcnt(0)
	v_readfirstlane_b32 s18, v6
	s_lshr_b32 s18, s18, 1
.Lslab_loop_as:
	global_load_dwordx4 v[28:31], v[24:25], off
	global_load_dwordx4 v[32:35], v[24:25], off offset:1024
	global_load_dwordx4 v[36:39], v[24:25], off offset:2048
	global_load_dwordx4 v[40:43], v[24:25], off offset:3072
	global_load_dwordx4 v[44:47], v[26:27], off
	global_load_dwordx4 v[48:51], v[26:27], off offset:1024
	global_load_dwordx4 v[52:55], v[26:27], off offset:2048
	global_load_dwordx4 v[56:59], v[26:27], off offset:3072
	v_lshl_add_u64 v[24:25], v[24:25], 0, s[12:13]
	v_lshl_add_u64 v[26:27], v[26:27], 0, s[12:13]
	s_waitcnt vmcnt(0)
	v_pk_add_f32 v[8:9], v[8:9], v[28:29]
	v_pk_add_f32 v[10:11], v[10:11], v[30:31]
	v_pk_add_f32 v[12:13], v[12:13], v[32:33]
	v_pk_add_f32 v[14:15], v[14:15], v[34:35]
	v_pk_add_f32 v[16:17], v[16:17], v[36:37]
	v_pk_add_f32 v[18:19], v[18:19], v[38:39]
	v_pk_add_f32 v[20:21], v[20:21], v[40:41]
	v_pk_add_f32 v[22:23], v[22:23], v[42:43]
	v_pk_add_f32 v[8:9], v[8:9], v[44:45]
	v_pk_add_f32 v[10:11], v[10:11], v[46:47]
	v_pk_add_f32 v[12:13], v[12:13], v[48:49]
	v_pk_add_f32 v[14:15], v[14:15], v[50:51]
	v_pk_add_f32 v[16:17], v[16:17], v[52:53]
	v_pk_add_f32 v[18:19], v[18:19], v[54:55]
	v_pk_add_f32 v[20:21], v[20:21], v[56:57]
	v_pk_add_f32 v[22:23], v[22:23], v[58:59]
	s_add_i32 s18, s18, -1
	s_cmp_lg_u32 s18, 0
	s_cbranch_scc1 .Lslab_loop_as
	v_readlane_b32 s14, v250, 15
	v_readlane_b32 s18, v250, 16
	s_add_u32 s12, s14, 0xb506000
	s_addc_u32 s13, s18, 0
	v_lshl_add_u64 v[4:5], s[12:13], 0, v[2:3]
	global_store_dwordx4 v[4:5], v[8:11], off
	global_store_dwordx4 v[4:5], v[12:15], off offset:1024
	global_store_dwordx4 v[4:5], v[16:19], off offset:2048
	global_store_dwordx4 v[4:5], v[20:23], off offset:3072
.Lslab_done_a:
	s_waitcnt vmcnt(0)
.Lslab_skip_a:
	v_and_b32_e32 v1, 64, v235
	v_add_u32_e32 v1, 64, v1
	v_xor_b32_e32 v2, 1, v235
	v_cmp_lt_i32_e32 vcc, v2, v1
	v_and_b32_e32 v0, 63, v0
	v_readlane_b32 s12, v250, 41
	v_cndmask_b32_e32 v2, v235, v2, vcc
	s_waitcnt vmcnt(2)
	v_lshlrev_b32_e32 v60, 2, v2
	v_xor_b32_e32 v2, 2, v235
	v_cmp_lt_i32_e32 vcc, v2, v1
	v_lshlrev_b32_e32 v80, 4, v0
	v_readlane_b32 s13, v250, 42
	v_cndmask_b32_e32 v2, v235, v2, vcc
	v_lshlrev_b32_e32 v61, 2, v2
	v_xor_b32_e32 v2, 4, v235
	v_cmp_lt_i32_e32 vcc, v2, v1
	v_lshl_add_u64 v[36:37], s[12:13], 0, v[80:81]
	v_readlane_b32 s12, v254, 15
	v_cndmask_b32_e32 v2, v235, v2, vcc
	s_waitcnt vmcnt(1)
	v_lshlrev_b32_e32 v62, 2, v2
	v_xor_b32_e32 v2, 8, v235
	v_cmp_lt_i32_e32 vcc, v2, v1
	v_lshlrev_b32_e32 v0, 3, v0
	v_readlane_b32 s13, v254, 16
	v_cndmask_b32_e32 v2, v235, v2, vcc
	v_lshlrev_b32_e32 v63, 2, v2
	v_xor_b32_e32 v2, 16, v235
	v_cmp_lt_i32_e32 vcc, v2, v1
	v_lshl_add_u64 v[38:39], s[4:5], 0, v[80:81]
	s_nop 0
	v_cndmask_b32_e32 v2, v235, v2, vcc
	v_lshlrev_b32_e32 v64, 2, v2
	v_xor_b32_e32 v2, 32, v235
	v_cmp_lt_i32_e32 vcc, v2, v1
	s_nop 1
	v_cndmask_b32_e32 v1, v235, v2, vcc
	v_lshlrev_b32_e32 v65, 2, v1
	v_mov_b32_e32 v1, v81
	v_lshl_add_u64 v[40:41], s[12:13], 0, v[0:1]
	v_readlane_b32 s12, v254, 40
	v_readlane_b32 s13, v254, 41
	s_nop 1
	v_lshl_add_u64 v[42:43], s[12:13], 0, v[80:81]
	v_readlane_b32 s12, v254, 27
	v_readlane_b32 s13, v254, 28
	s_nop 1
	v_lshl_add_u64 v[44:45], s[12:13], 0, v[0:1]
	v_readlane_b32 s12, v250, 6
	s_mov_b32 s7, s12
	v_readlane_b32 s13, v250, 7
	s_branch .LBB0_3021

.LBB0_3319:
	v_lshl_add_u32 v140, s54, 8, v154
	v_ashrrev_i32_e32 v141, 31, v140
	v_readlane_b32 s38, v250, 41
	v_lshl_or_b32 v142, s56, 8, v156
	v_lshlrev_b64 v[144:145], 12, v[140:141]
	v_readlane_b32 s39, v250, 42
	v_ashrrev_i32_e32 v143, 31, v142
	v_or_b32_e32 v148, 16, v140
	v_lshl_add_u64 v[152:153], s[38:39], 0, v[144:145]
	v_or_b32_e32 v146, 32, v140
	v_or_b32_e32 v144, 48, v140
	v_lshl_add_u64 v[150:151], v[142:143], 2, v[152:153]
	s_mov_b64 s[38:39], -1
	s_andn2_b64 vcc, exec, s[58:59]
	v_lshlrev_b64 v[142:143], 2, v[142:143]
	v_ashrrev_i32_e32 v149, 31, v148
	v_ashrrev_i32_e32 v147, 31, v146
	v_ashrrev_i32_e32 v145, 31, v144
	s_cbranch_vccnz .LBB0_3322
	v_mov_b32_e32 v133, v132
	s_add_i32 s38, s70, -1
	s_mul_i32 s38, s38, s96
	s_add_i32 s38, s38, s2
	s_addk_i32 s38, 0xff00
	s_lshr_b32 s38, s38, 2
	s_lshl_b32 s38, s38, 20
	s_add_u32 s38, s38, 0x1bfe0000
	s_mov_b32 s39, 0
	v_lshl_add_u64 v[208:209], v[150:151], 0, s[38:39]
	v_pk_mul_f32 v[160:161], v[134:135], v[126:127]
	v_pk_mul_f32 v[162:163], v[132:133], v[128:129]
	global_store_dwordx4 v[208:209], v[160:163], off
	v_pk_mul_f32 v[164:165], v[134:135], v[122:123]
	v_pk_mul_f32 v[166:167], v[132:133], v[124:125]
	global_store_dwordx4 v[208:209], v[164:167], off offset:64
	v_pk_mul_f32 v[168:169], v[134:135], v[118:119]
	v_pk_mul_f32 v[170:171], v[132:133], v[120:121]
	global_store_dwordx4 v[208:209], v[168:171], off offset:512
	v_pk_mul_f32 v[172:173], v[134:135], v[114:115]
	v_pk_mul_f32 v[174:175], v[132:133], v[116:117]
	global_store_dwordx4 v[208:209], v[172:175], off offset:576
	s_mov_b64 s[38:39], 0x10000
	v_lshl_add_u64 v[210:211], v[208:209], 0, s[38:39]
	v_pk_mul_f32 v[160:161], v[134:135], v[110:111]
	v_pk_mul_f32 v[162:163], v[132:133], v[112:113]
	global_store_dwordx4 v[210:211], v[160:163], off
	v_pk_mul_f32 v[164:165], v[134:135], v[106:107]
	v_pk_mul_f32 v[166:167], v[132:133], v[108:109]
	global_store_dwordx4 v[210:211], v[164:167], off offset:64
	v_pk_mul_f32 v[168:169], v[134:135], v[102:103]
	v_pk_mul_f32 v[170:171], v[132:133], v[104:105]
	global_store_dwordx4 v[210:211], v[168:171], off offset:512
	v_pk_mul_f32 v[172:173], v[134:135], v[98:99]
	v_pk_mul_f32 v[174:175], v[132:133], v[100:101]
	global_store_dwordx4 v[210:211], v[172:175], off offset:576
	s_mov_b64 s[38:39], 0x20000
	v_lshl_add_u64 v[178:179], v[208:209], 0, s[38:39]
	v_pk_mul_f32 v[160:161], v[134:135], v[94:95]
	v_pk_mul_f32 v[162:163], v[132:133], v[96:97]
	global_store_dwordx4 v[178:179], v[160:163], off
	v_pk_mul_f32 v[164:165], v[134:135], v[90:91]
	v_pk_mul_f32 v[166:167], v[132:133], v[92:93]
	global_store_dwordx4 v[178:179], v[164:167], off offset:64
	v_pk_mul_f32 v[168:169], v[134:135], v[86:87]
	v_pk_mul_f32 v[170:171], v[132:133], v[88:89]
	global_store_dwordx4 v[178:179], v[168:171], off offset:512
	v_pk_mul_f32 v[172:173], v[134:135], v[82:83]
	v_pk_mul_f32 v[174:175], v[132:133], v[84:85]
	global_store_dwordx4 v[178:179], v[172:175], off offset:576
	s_mov_b64 s[38:39], 0x30000
	v_lshl_add_u64 v[210:211], v[208:209], 0, s[38:39]
	v_pk_mul_f32 v[160:161], v[134:135], v[76:77]
	v_pk_mul_f32 v[162:163], v[132:133], v[78:79]
	global_store_dwordx4 v[210:211], v[160:163], off
	v_pk_mul_f32 v[164:165], v[134:135], v[72:73]
	v_pk_mul_f32 v[166:167], v[132:133], v[74:75]
	global_store_dwordx4 v[210:211], v[164:167], off offset:64
	v_pk_mul_f32 v[168:169], v[134:135], v[68:69]
	v_pk_mul_f32 v[170:171], v[132:133], v[70:71]
	global_store_dwordx4 v[210:211], v[168:171], off offset:512
	v_pk_mul_f32 v[172:173], v[134:135], v[64:65]
	v_pk_mul_f32 v[174:175], v[132:133], v[66:67]
	global_store_dwordx4 v[210:211], v[172:175], off offset:576
	s_mov_b64 s[38:39], 0x80000
	v_lshl_add_u64 v[178:179], v[208:209], 0, s[38:39]
	v_pk_mul_f32 v[160:161], v[134:135], v[60:61]
	v_pk_mul_f32 v[162:163], v[132:133], v[62:63]
	global_store_dwordx4 v[178:179], v[160:163], off
	v_pk_mul_f32 v[164:165], v[134:135], v[56:57]
	v_pk_mul_f32 v[166:167], v[132:133], v[58:59]
	global_store_dwordx4 v[178:179], v[164:167], off offset:64
	v_pk_mul_f32 v[168:169], v[134:135], v[52:53]
	v_pk_mul_f32 v[170:171], v[132:133], v[54:55]
	global_store_dwordx4 v[178:179], v[168:171], off offset:512
	v_pk_mul_f32 v[172:173], v[134:135], v[48:49]
	v_pk_mul_f32 v[174:175], v[132:133], v[50:51]
	global_store_dwordx4 v[178:179], v[172:175], off offset:576
	s_mov_b64 s[38:39], 0x90000
	v_lshl_add_u64 v[210:211], v[208:209], 0, s[38:39]
	v_pk_mul_f32 v[160:161], v[134:135], v[44:45]
	v_pk_mul_f32 v[162:163], v[132:133], v[46:47]
	global_store_dwordx4 v[210:211], v[160:163], off
	v_pk_mul_f32 v[164:165], v[134:135], v[40:41]
	v_pk_mul_f32 v[166:167], v[132:133], v[42:43]
	global_store_dwordx4 v[210:211], v[164:167], off offset:64
	v_pk_mul_f32 v[168:169], v[134:135], v[36:37]
	v_pk_mul_f32 v[170:171], v[132:133], v[38:39]
	global_store_dwordx4 v[210:211], v[168:171], off offset:512
	v_pk_mul_f32 v[172:173], v[134:135], v[32:33]
	v_pk_mul_f32 v[174:175], v[132:133], v[34:35]
	global_store_dwordx4 v[210:211], v[172:175], off offset:576
	s_mov_b64 s[38:39], 0xa0000
	v_lshl_add_u64 v[178:179], v[208:209], 0, s[38:39]
	v_pk_mul_f32 v[160:161], v[134:135], v[28:29]
	v_pk_mul_f32 v[162:163], v[132:133], v[30:31]
	global_store_dwordx4 v[178:179], v[160:163], off
	v_pk_mul_f32 v[164:165], v[134:135], v[24:25]
	v_pk_mul_f32 v[166:167], v[132:133], v[26:27]
	global_store_dwordx4 v[178:179], v[164:167], off offset:64
	v_pk_mul_f32 v[168:169], v[134:135], v[20:21]
	v_pk_mul_f32 v[170:171], v[132:133], v[22:23]
	global_store_dwordx4 v[178:179], v[168:171], off offset:512
	v_pk_mul_f32 v[172:173], v[134:135], v[16:17]
	v_pk_mul_f32 v[174:175], v[132:133], v[18:19]
	global_store_dwordx4 v[178:179], v[172:175], off offset:576
	s_mov_b64 s[38:39], 0xb0000
	v_lshl_add_u64 v[210:211], v[208:209], 0, s[38:39]
	v_pk_mul_f32 v[160:161], v[134:135], v[12:13]
	v_pk_mul_f32 v[162:163], v[132:133], v[14:15]
	global_store_dwordx4 v[210:211], v[160:163], off
	v_pk_mul_f32 v[164:165], v[134:135], v[8:9]
	v_pk_mul_f32 v[166:167], v[132:133], v[10:11]
	global_store_dwordx4 v[210:211], v[164:167], off offset:64
	v_pk_mul_f32 v[168:169], v[134:135], v[4:5]
	v_pk_mul_f32 v[170:171], v[132:133], v[6:7]
	global_store_dwordx4 v[210:211], v[168:171], off offset:512
	v_pk_mul_f32 v[172:173], v[134:135], v[0:1]
	v_pk_mul_f32 v[174:175], v[132:133], v[2:3]
	global_store_dwordx4 v[210:211], v[172:175], off offset:576
	v_mov_b32_e32 v177, 16
	v_readlane_b32 s38, v250, 41
	v_readlane_b32 s39, v250, 42
	s_add_u32 s38, s38, 0x20fe0000
	s_addc_u32 s39, s39, 0
	v_mov_b32_e32 v176, 0
	s_nop 3
	global_store_dword v176, v177, s[38:39]
	s_cbranch_execz .LBB0_3323

.LBB0_3452:
	v_readlane_b32 s26, v250, 6
	s_cmp_gt_u32 s26, 0xff
	s_cbranch_scc1 .Lslab_skip_b
	v_and_b32_e32 v2, 63, v226
	v_lshlrev_b32_e32 v2, 4, v2
	v_lshl_add_u32 v60, s26, 13, v2
	v_mov_b32_e32 v61, 0
	v_lshl_add_u32 v2, s26, 12, v2
	v_mov_b32_e32 v3, 0
	v_readlane_b32 s27, v254, 55
	s_cmp_eq_u32 s27, 0
	s_cbranch_scc1 .Lslab_b_l0
	v_readlane_b32 s26, v250, 15
	v_readlane_b32 s27, v250, 16
	s_add_u32 s18, s26, 0xb506000
	s_addc_u32 s19, s27, 0
	v_lshl_add_u64 v[4:5], s[18:19], 0, v[2:3]
	global_load_dwordx4 v[8:11], v[4:5], off sc1
	global_load_dwordx4 v[12:15], v[4:5], off offset:1024 sc1
	global_load_dwordx4 v[16:19], v[4:5], off offset:2048 sc1
	global_load_dwordx4 v[20:23], v[4:5], off offset:3072 sc1
	v_readlane_b32 s26, v250, 15
	v_readlane_b32 s27, v250, 16
	s_add_u32 s18, s26, 0x284e6000
	s_addc_u32 s19, s27, 0
	global_load_dword v6, v3, s[18:19] sc1
	v_readlane_b32 s26, v250, 15
	v_readlane_b32 s27, v250, 16
	s_add_u32 s18, s26, 0x274e6000
	s_addc_u32 s19, s27, 0
	v_lshl_add_u64 v[24:25], s[18:19], 0, v[2:3]
	s_mov_b64 s[18:19], 0x100000
	v_lshl_add_u64 v[26:27], v[24:25], 0, s[18:19]
	s_mov_b64 s[18:19], 0x200000
	s_waitcnt vmcnt(0)
	v_readfirstlane_b32 s27, v6
	s_lshr_b32 s27, s27, 1
.Lslab_loop_bn:
	global_load_dwordx4 v[28:31], v[24:25], off
	global_load_dwordx4 v[32:35], v[24:25], off offset:1024
	global_load_dwordx4 v[36:39], v[24:25], off offset:2048
	global_load_dwordx4 v[40:43], v[24:25], off offset:3072
	global_load_dwordx4 v[44:47], v[26:27], off
	global_load_dwordx4 v[48:51], v[26:27], off offset:1024
	global_load_dwordx4 v[52:55], v[26:27], off offset:2048
	global_load_dwordx4 v[56:59], v[26:27], off offset:3072
	v_lshl_add_u64 v[24:25], v[24:25], 0, s[18:19]
	v_lshl_add_u64 v[26:27], v[26:27], 0, s[18:19]
	s_waitcnt vmcnt(0)
	v_pk_add_f32 v[8:9], v[8:9], v[28:29]
	v_pk_add_f32 v[10:11], v[10:11], v[30:31]
	v_pk_add_f32 v[12:13], v[12:13], v[32:33]
	v_pk_add_f32 v[14:15], v[14:15], v[34:35]
	v_pk_add_f32 v[16:17], v[16:17], v[36:37]
	v_pk_add_f32 v[18:19], v[18:19], v[38:39]
	v_pk_add_f32 v[20:21], v[20:21], v[40:41]
	v_pk_add_f32 v[22:23], v[22:23], v[42:43]
	v_pk_add_f32 v[8:9], v[8:9], v[44:45]
	v_pk_add_f32 v[10:11], v[10:11], v[46:47]
	v_pk_add_f32 v[12:13], v[12:13], v[48:49]
	v_pk_add_f32 v[14:15], v[14:15], v[50:51]
	v_pk_add_f32 v[16:17], v[16:17], v[52:53]
	v_pk_add_f32 v[18:19], v[18:19], v[54:55]
	v_pk_add_f32 v[20:21], v[20:21], v[56:57]
	v_pk_add_f32 v[22:23], v[22:23], v[58:59]
	s_add_i32 s27, s27, -1
	s_cmp_lg_u32 s27, 0
	s_cbranch_scc1 .Lslab_loop_bn
	v_readlane_b32 s26, v250, 15
	v_readlane_b32 s27, v250, 16
	s_add_u32 s18, s26, 0xb506000
	s_addc_u32 s19, s27, 0
	v_lshl_add_u64 v[4:5], s[18:19], 0, v[2:3]
	global_store_dwordx4 v[4:5], v[8:11], off
	global_store_dwordx4 v[4:5], v[12:15], off offset:1024
	global_store_dwordx4 v[4:5], v[16:19], off offset:2048
	global_store_dwordx4 v[4:5], v[20:23], off offset:3072
	s_branch .Lslab_done_b
.Lslab_b_l0:
	v_readlane_b32 s26, v250, 15
	v_readlane_b32 s27, v250, 16
	s_add_u32 s18, s26, 0xb506000
	s_addc_u32 s19, s27, 0
	v_lshl_add_u64 v[4:5], s[18:19], 0, v[2:3]
	global_load_dwordx4 v[8:11], v[4:5], off sc1
	global_load_dwordx4 v[12:15], v[4:5], off offset:1024 sc1
	global_load_dwordx4 v[16:19], v[4:5], off offset:2048 sc1
	global_load_dwordx4 v[20:23], v[4:5], off offset:3072 sc1
	v_readlane_b32 s26, v250, 15
	v_readlane_b32 s27, v250, 16
	s_add_u32 s18, s26, 0x284e6000
	s_addc_u32 s19, s27, 0
	global_load_dword v6, v3, s[18:19] sc1
	v_readlane_b32 s26, v250, 15
	v_readlane_b32 s27, v250, 16
	s_add_u32 s18, s26, 0x274e6000
	s_addc_u32 s19, s27, 0
	v_lshl_add_u64 v[24:25], s[18:19], 0, v[2:3]
	s_mov_b64 s[18:19], 0x100000
	v_lshl_add_u64 v[26:27], v[24:25], 0, s[18:19]
	s_mov_b64 s[18:19], 0x200000
	s_waitcnt vmcnt(0)
	v_readfirstlane_b32 s27, v6
	s_lshr_b32 s27, s27, 1
.Lslab_loop_br1:
	global_load_dwordx4 v[28:31], v[24:25], off
	global_load_dwordx4 v[32:35], v[24:25], off offset:1024
	global_load_dwordx4 v[36:39], v[24:25], off offset:2048
	global_load_dwordx4 v[40:43], v[24:25], off offset:3072
	global_load_dwordx4 v[44:47], v[26:27], off
	global_load_dwordx4 v[48:51], v[26:27], off offset:1024
	global_load_dwordx4 v[52:55], v[26:27], off offset:2048
	global_load_dwordx4 v[56:59], v[26:27], off offset:3072
	v_lshl_add_u64 v[24:25], v[24:25], 0, s[18:19]
	v_lshl_add_u64 v[26:27], v[26:27], 0, s[18:19]
	s_waitcnt vmcnt(0)
	v_pk_add_f32 v[8:9], v[8:9], v[28:29]
	v_pk_add_f32 v[10:11], v[10:11], v[30:31]
	v_pk_add_f32 v[12:13], v[12:13], v[32:33]
	v_pk_add_f32 v[14:15], v[14:15], v[34:35]
	v_pk_add_f32 v[16:17], v[16:17], v[36:37]
	v_pk_add_f32 v[18:19], v[18:19], v[38:39]
	v_pk_add_f32 v[20:21], v[20:21], v[40:41]
	v_pk_add_f32 v[22:23], v[22:23], v[42:43]
	v_pk_add_f32 v[8:9], v[8:9], v[44:45]
	v_pk_add_f32 v[10:11], v[10:11], v[46:47]
	v_pk_add_f32 v[12:13], v[12:13], v[48:49]
	v_pk_add_f32 v[14:15], v[14:15], v[50:51]
	v_pk_add_f32 v[16:17], v[16:17], v[52:53]
	v_pk_add_f32 v[18:19], v[18:19], v[54:55]
	v_pk_add_f32 v[20:21], v[20:21], v[56:57]
	v_pk_add_f32 v[22:23], v[22:23], v[58:59]
	s_add_i32 s27, s27, -1
	s_cmp_lg_u32 s27, 0
	s_cbranch_scc1 .Lslab_loop_br1
	v_readlane_b32 s26, v250, 13
	v_readlane_b32 s27, v250, 14
	s_add_u32 s18, s26, 0x1000
	s_addc_u32 s19, s27, 0
	v_lshl_add_u64 v[4:5], s[18:19], 0, v[60:61]
	global_store_dwordx4 v[4:5], v[8:11], off
	global_store_dwordx4 v[4:5], v[12:15], off offset:1024
	global_store_dwordx4 v[4:5], v[16:19], off offset:2048
	global_store_dwordx4 v[4:5], v[20:23], off offset:3072
	v_readlane_b32 s26, v250, 6
	s_cmp_gt_u32 s26, 0x7f
	s_cbranch_scc1 .Lslab_done_b
	s_cmp_eq_u32 s26, 0
	s_cbranch_scc1 .Lslab_b_row0plain
	v_readlane_b32 s26, v250, 15
	v_readlane_b32 s27, v250, 16
	s_add_u32 s18, s26, 0xb505000
	s_addc_u32 s19, s27, 0
	v_lshl_add_u64 v[4:5], s[18:19], 0, v[2:3]
	global_load_dwordx4 v[8:11], v[4:5], off sc1
	global_load_dwordx4 v[12:15], v[4:5], off offset:1024 sc1
	global_load_dwordx4 v[16:19], v[4:5], off offset:2048 sc1
	global_load_dwordx4 v[20:23], v[4:5], off offset:3072 sc1
	v_readlane_b32 s26, v250, 15
	v_readlane_b32 s27, v250, 16
	s_add_u32 s18, s26, 0x284e6000
	s_addc_u32 s19, s27, 0
	global_load_dword v6, v3, s[18:19] sc1
	v_readlane_b32 s26, v250, 15
	v_readlane_b32 s27, v250, 16
	s_add_u32 s18, s26, 0x274e5000
	s_addc_u32 s19, s27, 0
	v_lshl_add_u64 v[24:25], s[18:19], 0, v[2:3]
	s_mov_b64 s[18:19], 0x100000
	v_lshl_add_u64 v[26:27], v[24:25], 0, s[18:19]
	s_mov_b64 s[18:19], 0x200000
	s_waitcnt vmcnt(0)
	v_readfirstlane_b32 s27, v6
	s_lshr_b32 s27, s27, 1
.Lslab_loop_br0:
	global_load_dwordx4 v[28:31], v[24:25], off
	global_load_dwordx4 v[32:35], v[24:25], off offset:1024
	global_load_dwordx4 v[36:39], v[24:25], off offset:2048
	global_load_dwordx4 v[40:43], v[24:25], off offset:3072
	global_load_dwordx4 v[44:47], v[26:27], off
	global_load_dwordx4 v[48:51], v[26:27], off offset:1024
	global_load_dwordx4 v[52:55], v[26:27], off offset:2048
	global_load_dwordx4 v[56:59], v[26:27], off offset:3072
	v_lshl_add_u64 v[24:25], v[24:25], 0, s[18:19]
	v_lshl_add_u64 v[26:27], v[26:27], 0, s[18:19]
	s_waitcnt vmcnt(0)
	v_pk_add_f32 v[8:9], v[8:9], v[28:29]
	v_pk_add_f32 v[10:11], v[10:11], v[30:31]
	v_pk_add_f32 v[12:13], v[12:13], v[32:33]
	v_pk_add_f32 v[14:15], v[14:15], v[34:35]
	v_pk_add_f32 v[16:17], v[16:17], v[36:37]
	v_pk_add_f32 v[18:19], v[18:19], v[38:39]
	v_pk_add_f32 v[20:21], v[20:21], v[40:41]
	v_pk_add_f32 v[22:23], v[22:23], v[42:43]
	v_pk_add_f32 v[8:9], v[8:9], v[44:45]
	v_pk_add_f32 v[10:11], v[10:11], v[46:47]
	v_pk_add_f32 v[12:13], v[12:13], v[48:49]
	v_pk_add_f32 v[14:15], v[14:15], v[50:51]
	v_pk_add_f32 v[16:17], v[16:17], v[52:53]
	v_pk_add_f32 v[18:19], v[18:19], v[54:55]
	v_pk_add_f32 v[20:21], v[20:21], v[56:57]
	v_pk_add_f32 v[22:23], v[22:23], v[58:59]
	s_add_i32 s27, s27, -1
	s_cmp_lg_u32 s27, 0
	s_cbranch_scc1 .Lslab_loop_br0
	v_readlane_b32 s26, v250, 13
	v_readlane_b32 s27, v250, 14
	s_add_u32 s18, s26, 0x0
	s_addc_u32 s19, s27, 0
	v_lshl_add_u64 v[4:5], s[18:19], 0, v[60:61]
	global_store_dwordx4 v[4:5], v[8:11], off
	global_store_dwordx4 v[4:5], v[12:15], off offset:1024
	global_store_dwordx4 v[4:5], v[16:19], off offset:2048
	global_store_dwordx4 v[4:5], v[20:23], off offset:3072
	s_branch .Lslab_done_b
.Lslab_b_row0plain:
	v_readlane_b32 s26, v250, 15
	v_readlane_b32 s27, v250, 16
	s_add_u32 s18, s26, 0xb505000
	s_addc_u32 s19, s27, 0
	v_lshl_add_u64 v[4:5], s[18:19], 0, v[2:3]
	global_load_dwordx4 v[8:11], v[4:5], off sc1
	global_load_dwordx4 v[12:15], v[4:5], off offset:1024 sc1
	global_load_dwordx4 v[16:19], v[4:5], off offset:2048 sc1
	global_load_dwordx4 v[20:23], v[4:5], off offset:3072 sc1
	s_waitcnt vmcnt(0)
	v_readlane_b32 s26, v250, 13
	v_readlane_b32 s27, v250, 14
	s_add_u32 s18, s26, 0x0
	s_addc_u32 s19, s27, 0
	v_lshl_add_u64 v[4:5], s[18:19], 0, v[60:61]
	global_store_dwordx4 v[4:5], v[8:11], off
	global_store_dwordx4 v[4:5], v[12:15], off offset:1024
	global_store_dwordx4 v[4:5], v[16:19], off offset:2048
	global_store_dwordx4 v[4:5], v[20:23], off offset:3072
.Lslab_done_b:
	s_waitcnt vmcnt(0)
.Lslab_skip_b:
	v_readlane_b32 s26, v255, 40
	v_mov_b32_e32 v0, v226
	v_readlane_b32 s27, v255, 41
	s_mov_b64 s[18:19], -1
	v_and_b32_e32 v148, 63, v0
	s_and_b64 vcc, exec, s[26:27]
	v_readlane_b32 s46, v253, 9
	v_readlane_b32 s47, v253, 10
	s_cbranch_vccz .LBB0_3475
	s_and_b64 vcc, exec, s[4:5]
	s_cbranch_vccz .LBB0_3460
	v_readlane_b32 s18, v252, 30
	v_readlane_b32 s19, v252, 31
	s_andn2_b64 vcc, exec, s[18:19]
	s_cbranch_vccnz .LBB0_3459
	v_and_b32_e32 v0, 64, v235
	v_add_u32_e32 v0, 64, v0
	v_xor_b32_e32 v1, 1, v235
	v_cmp_lt_i32_e32 vcc, v1, v0
	v_readlane_b32 s18, v250, 41
	v_lshlrev_b32_e32 v80, 4, v148
	v_cndmask_b32_e32 v1, v235, v1, vcc
	s_waitcnt vmcnt(2)
	v_lshlrev_b32_e32 v60, 2, v1
	v_xor_b32_e32 v1, 2, v235
	v_cmp_lt_i32_e32 vcc, v1, v0
	v_readlane_b32 s19, v250, 42
	v_lshl_add_u64 v[38:39], s[12:13], 0, v[80:81]
	v_cndmask_b32_e32 v1, v235, v1, vcc
	v_lshlrev_b32_e32 v61, 2, v1
	v_xor_b32_e32 v1, 4, v235
	v_cmp_lt_i32_e32 vcc, v1, v0
	v_lshl_add_u64 v[36:37], s[18:19], 0, v[80:81]
	v_readlane_b32 s18, v254, 15
	v_cndmask_b32_e32 v1, v235, v1, vcc
	s_waitcnt vmcnt(1)
	v_lshlrev_b32_e32 v62, 2, v1
	v_xor_b32_e32 v1, 8, v235
	v_cmp_lt_i32_e32 vcc, v1, v0
	v_readlane_b32 s19, v254, 16
	s_nop 0
	v_cndmask_b32_e32 v1, v235, v1, vcc
	v_lshlrev_b32_e32 v63, 2, v1
	v_xor_b32_e32 v1, 16, v235
	v_cmp_lt_i32_e32 vcc, v1, v0
	s_nop 1
	v_cndmask_b32_e32 v1, v235, v1, vcc
	v_lshlrev_b32_e32 v64, 2, v1
	v_xor_b32_e32 v1, 32, v235
	v_cmp_lt_i32_e32 vcc, v1, v0
	s_nop 1
	v_cndmask_b32_e32 v0, v235, v1, vcc
	v_lshlrev_b32_e32 v65, 2, v0
	v_lshlrev_b32_e32 v0, 3, v148
	v_mov_b32_e32 v1, v81
	v_lshl_add_u64 v[40:41], s[18:19], 0, v[0:1]
	v_readlane_b32 s18, v254, 40
	v_readlane_b32 s19, v254, 41
	s_nop 1
	v_lshl_add_u64 v[42:43], s[18:19], 0, v[80:81]
	v_readlane_b32 s18, v254, 27
	v_readlane_b32 s19, v254, 28
	s_nop 1
	v_lshl_add_u64 v[44:45], s[18:19], 0, v[0:1]
	v_readlane_b32 s18, v250, 6
	s_mov_b32 s7, s18
	v_readlane_b32 s19, v250, 7
	s_branch .LBB0_3457

.LBB0_3464:
	v_lshl_add_u64 v[82:83], s[78:79], 0, v[168:169]
	v_add_co_u32_e32 v82, vcc, 0x7506000, v82
	s_add_i32 s7, s92, 0x4080
	s_nop 0
	v_addc_co_u32_e32 v83, vcc, 0, v83, vcc
	s_cmpk_lt_i32 s92, 0xff80
	s_cbranch_scc1 .Lxm_plain_4096
	v_readlane_b32 vcc_lo, v250, 6
	v_and_b32_e32 v82, 63, v226
	v_lshlrev_b32_e32 v82, 4, v82
	v_lshl_add_u32 v82, vcc_lo, 13, v82
	v_add_u32_e32 v82, 0x1000, v82
	v_mov_b32_e32 v83, 0
	v_readlane_b32 vcc_lo, v250, 13
	v_readlane_b32 vcc_hi, v250, 14
	s_nop 1
	v_lshl_add_u64 v[82:83], vcc, 0, v[82:83]
.Lxm_plain_4096:
	global_load_dwordx4 v[100:103], v[82:83], off
	s_cmpk_gt_i32 s7, 0x407f
	s_waitcnt vmcnt(0)
	v_pk_mul_f32 v[104:105], v[102:103], v[102:103]
	v_pk_mul_f32 v[106:107], v[100:101], v[100:101]
	s_nop 0
	v_pk_mov_b32 v[108:109], v[106:107], v[104:105] op_sel:[1,0]
	v_mov_b32_e32 v107, v105
	v_pk_add_f32 v[116:117], v[108:109], v[106:107]
	global_load_dwordx4 v[104:107], v[82:83], off offset:1024
	s_waitcnt vmcnt(0)
	v_pk_mul_f32 v[108:109], v[106:107], v[106:107]
	v_pk_mul_f32 v[110:111], v[104:105], v[104:105]
	s_nop 0
	v_pk_mov_b32 v[112:113], v[110:111], v[108:109] op_sel:[1,0]
	v_mov_b32_e32 v111, v109
	v_pk_add_f32 v[118:119], v[112:113], v[110:111]
	global_load_dwordx4 v[108:111], v[82:83], off offset:2048
	global_load_dwordx4 v[112:115], v[82:83], off offset:3072
	v_pk_add_f32 v[82:83], v[116:117], v[116:117] op_sel:[0,1] op_sel_hi:[1,0]
	v_pk_add_f32 v[116:117], v[118:119], v[118:119] op_sel:[0,1] op_sel_hi:[1,0]
	global_load_dwordx4 v[128:131], v[152:153], off offset:2048
	global_load_dwordx4 v[124:127], v[152:153], off offset:3072
	s_waitcnt vmcnt(2)
	v_mul_f32_e32 v80, v112, v112
	v_mul_f32_e32 v120, v113, v113
	v_mov_b32_e32 v83, v80
	v_mov_b32_e32 v117, v120
	v_mul_f32_e32 v80, v109, v109
	v_pk_add_f32 v[82:83], v[82:83], v[116:117]
	v_pk_fma_f32 v[116:117], v[108:109], v[108:109], v[80:81] op_sel_hi:[1,1,0]
	v_mul_f32_e32 v80, v111, v111
	v_mul_f32_e32 v121, v114, v114
	v_mul_f32_e32 v122, v115, v115
	v_pk_fma_f32 v[118:119], v[110:111], v[110:111], v[80:81] op_sel_hi:[1,1,0]
	v_mov_b32_e32 v117, v121
	v_mov_b32_e32 v119, v122
	v_pk_add_f32 v[116:117], v[116:117], v[118:119]
	global_load_dwordx4 v[120:123], v[152:153], off offset:1024
	v_pk_add_f32 v[82:83], v[82:83], v[116:117]
	s_nop 0
	v_add_f32_e32 v80, v82, v83
	ds_bpermute_b32 v82, v149, v80
	s_waitcnt lgkmcnt(0)
	v_add_f32_e32 v80, v80, v82
	ds_bpermute_b32 v82, v171, v80
	s_waitcnt lgkmcnt(0)
	v_add_f32_e32 v80, v80, v82
	ds_bpermute_b32 v82, v172, v80
	s_waitcnt lgkmcnt(0)
	v_add_f32_e32 v80, v80, v82
	ds_bpermute_b32 v82, v173, v80
	s_waitcnt lgkmcnt(0)
	v_add_f32_e32 v80, v80, v82
	ds_bpermute_b32 v82, v174, v80
	s_waitcnt lgkmcnt(0)
	v_add_f32_e32 v80, v80, v82
	ds_bpermute_b32 v82, v175, v80
	s_waitcnt lgkmcnt(0)
	v_add_f32_e32 v80, v80, v82
	v_fmamk_f32 v80, v80, 0x3a800000, v231
	v_cmp_gt_f32_e32 vcc, s48, v80
	v_mul_f32_e32 v82, 0x4f800000, v80
	s_nop 0
	v_cndmask_b32_e32 v80, v80, v82, vcc
	v_sqrt_f32_e32 v82, v80
	s_nop 0
	v_add_u32_e32 v83, -1, v82
	v_fma_f32 v116, -v83, v82, v80
	v_cmp_ge_f32_e64 s[42:43], 0, v116
	v_add_u32_e32 v116, 1, v82
	s_nop 0
	v_cndmask_b32_e64 v83, v82, v83, s[42:43]
	v_fma_f32 v82, -v116, v82, v80
	v_cmp_lt_f32_e64 s[42:43], 0, v82
	s_nop 1
	v_cndmask_b32_e64 v82, v83, v116, s[42:43]
	v_mul_f32_e32 v83, 0x37800000, v82
	v_cndmask_b32_e32 v82, v82, v83, vcc
	v_cmp_class_f32_e32 vcc, v80, v230
	s_nop 1
	v_cndmask_b32_e32 v80, v82, v80, vcc
	v_div_scale_f32 v82, s[18:19], v80, v80, 1.0
	v_rcp_f32_e32 v83, v82
	s_nop 0
	v_fma_f32 v116, -v82, v83, 1.0
	v_fmac_f32_e32 v83, v116, v83
	v_div_scale_f32 v116, vcc, 1.0, v80, 1.0
	v_mul_f32_e32 v117, v116, v83
	v_fma_f32 v118, -v82, v117, v116
	v_fmac_f32_e32 v117, v118, v83
	v_fma_f32 v82, -v82, v117, v116
	v_div_fmas_f32 v82, v82, v83, v117
	global_load_dwordx4 v[116:119], v[152:153], off
	v_div_fixup_f32 v170, v82, v80, 1.0
	v_pk_mul_f32 v[82:83], v[100:101], v[170:171] op_sel_hi:[1,0]
	v_pk_mul_f32 v[100:101], v[102:103], v[170:171] op_sel_hi:[1,0]
	s_waitcnt vmcnt(0)
	v_pk_mul_f32 v[102:103], v[118:119], v[100:101]
	v_pk_mul_f32 v[100:101], v[116:117], v[82:83]
	v_pk_mul_f32 v[82:83], v[104:105], v[170:171] op_sel_hi:[1,0]
	v_pk_mul_f32 v[104:105], v[106:107], v[170:171] op_sel_hi:[1,0]
	s_nop 0
	v_pk_mul_f32 v[106:107], v[122:123], v[104:105]
	v_pk_mul_f32 v[104:105], v[120:121], v[82:83]
	v_pk_mul_f32 v[82:83], v[108:109], v[170:171] op_sel_hi:[1,0]
	v_pk_mul_f32 v[108:109], v[110:111], v[170:171] op_sel_hi:[1,0]
	s_nop 0
	v_pk_mul_f32 v[110:111], v[130:131], v[108:109]
	v_pk_mul_f32 v[108:109], v[128:129], v[82:83]
	s_cbranch_scc0 .LBB0_3466
	s_lshl_b64 s[18:19], s[92:93], 12
	v_lshl_add_u64 v[140:141], v[154:155], 0, s[18:19]
	v_lshl_add_u64 v[82:83], v[156:157], 0, s[18:19]
	global_load_dwordx4 v[136:139], v[140:141], off
	s_nop 0
	global_store_dwordx4 v[82:83], v[100:103], off
	global_load_dwordx4 v[144:147], v[140:141], off offset:1024
	s_mov_b64 s[18:19], -1
	global_store_dwordx4 v[82:83], v[104:107], off offset:1024
	global_load_dwordx4 v[132:135], v[140:141], off offset:2048
	s_nop 0
	global_store_dwordx4 v[82:83], v[108:111], off offset:2048
	global_load_dwordx4 v[140:143], v[140:141], off offset:3072
	s_cbranch_execz .LBB0_3467
	s_branch .LBB0_3471

.LBB0_3467:
	s_mul_hi_i32 s7, s7, 0xfe03f81
	s_lshr_b32 s14, s7, 31
	s_ashr_i32 s7, s7, 7
	s_add_i32 s44, s7, s14
	s_mul_i32 s7, s44, 0xfffff7f0
	s_add_i32 s7, s92, s7
	s_add_i32 s14, s7, 0x4080
	s_cmp_lt_i32 s14, 1
	s_cbranch_scc1 .LBB0_3473
	s_add_i32 s26, s92, 0x407f
	s_ashr_i32 s27, s26, 31
	s_lshl_b64 s[26:27], s[26:27], 12
	v_lshl_add_u64 v[82:83], v[150:151], 0, s[26:27]
	s_cmpk_lt_i32 s92, 0xff80
	s_cbranch_scc1 .Lxm_plain_0
	v_readlane_b32 vcc_lo, v250, 6
	v_and_b32_e32 v82, 63, v226
	v_lshlrev_b32_e32 v82, 4, v82
	v_lshl_add_u32 v82, vcc_lo, 13, v82
	v_mov_b32_e32 v83, 0
	v_readlane_b32 vcc_lo, v250, 13
	v_readlane_b32 vcc_hi, v250, 14
	s_nop 1
	v_lshl_add_u64 v[82:83], vcc, 0, v[82:83]
.Lxm_plain_0:
	global_load_dwordx4 v[136:139], v[82:83], off
	global_load_dwordx4 v[144:147], v[82:83], off offset:1024
	s_waitcnt vmcnt(1)
	v_pk_mul_f32 v[132:133], v[138:139], v[138:139]
	v_pk_mul_f32 v[134:135], v[136:137], v[136:137]
	s_nop 0
	v_pk_mov_b32 v[140:141], v[134:135], v[132:133] op_sel:[1,0]
	v_mov_b32_e32 v135, v133
	v_pk_add_f32 v[158:159], v[140:141], v[134:135]
	s_waitcnt vmcnt(0)
	v_pk_mul_f32 v[132:133], v[146:147], v[146:147]
	v_pk_mul_f32 v[134:135], v[144:145], v[144:145]
	s_nop 0
	v_pk_mov_b32 v[140:141], v[134:135], v[132:133] op_sel:[1,0]
	v_mov_b32_e32 v135, v133
	v_pk_add_f32 v[160:161], v[140:141], v[134:135]
	global_load_dwordx4 v[132:135], v[82:83], off offset:2048
	global_load_dwordx4 v[140:143], v[82:83], off offset:3072
	v_pk_add_f32 v[82:83], v[158:159], v[158:159] op_sel:[0,1] op_sel_hi:[1,0]
	v_pk_add_f32 v[158:159], v[160:161], v[160:161] op_sel:[0,1] op_sel_hi:[1,0]
	s_waitcnt vmcnt(0)
	v_mul_f32_e32 v80, v140, v140
	v_mul_f32_e32 v176, v141, v141
	v_mov_b32_e32 v83, v80
	v_mov_b32_e32 v159, v176
	v_mul_f32_e32 v80, v133, v133
	v_pk_add_f32 v[82:83], v[82:83], v[158:159]
	v_pk_fma_f32 v[158:159], v[132:133], v[132:133], v[80:81] op_sel_hi:[1,1,0]
	v_mul_f32_e32 v80, v135, v135
	v_mul_f32_e32 v177, v142, v142
	v_mul_f32_e32 v178, v143, v143
	v_pk_fma_f32 v[160:161], v[134:135], v[134:135], v[80:81] op_sel_hi:[1,1,0]
	v_mov_b32_e32 v159, v177
	v_mov_b32_e32 v161, v178
	v_pk_add_f32 v[158:159], v[158:159], v[160:161]
	s_nop 0
	v_pk_add_f32 v[82:83], v[82:83], v[158:159]
	s_nop 0
	v_add_f32_e32 v80, v82, v83
	ds_bpermute_b32 v82, v149, v80
	s_waitcnt lgkmcnt(0)
	v_add_f32_e32 v80, v80, v82
	ds_bpermute_b32 v82, v171, v80
	s_waitcnt lgkmcnt(0)
	v_add_f32_e32 v80, v80, v82
	ds_bpermute_b32 v82, v172, v80
	s_waitcnt lgkmcnt(0)
	v_add_f32_e32 v80, v80, v82
	ds_bpermute_b32 v82, v173, v80
	s_waitcnt lgkmcnt(0)
	v_add_f32_e32 v80, v80, v82
	ds_bpermute_b32 v82, v174, v80
	s_waitcnt lgkmcnt(0)
	v_add_f32_e32 v80, v80, v82
	ds_bpermute_b32 v82, v175, v80
	s_waitcnt lgkmcnt(0)
	v_add_f32_e32 v80, v80, v82
	v_fmamk_f32 v80, v80, 0x3a800000, v231
	v_cmp_gt_f32_e32 vcc, s48, v80
	v_mul_f32_e32 v82, 0x4f800000, v80
	s_nop 0
	v_cndmask_b32_e32 v80, v80, v82, vcc
	v_sqrt_f32_e32 v82, v80
	s_nop 0
	v_add_u32_e32 v83, -1, v82
	v_fma_f32 v158, -v83, v82, v80
	v_cmp_ge_f32_e64 s[42:43], 0, v158
	v_add_u32_e32 v158, 1, v82
	s_nop 0
	v_cndmask_b32_e64 v83, v82, v83, s[42:43]
	v_fma_f32 v82, -v158, v82, v80
	v_cmp_lt_f32_e64 s[42:43], 0, v82
	s_nop 1
	v_cndmask_b32_e64 v82, v83, v158, s[42:43]
	v_mul_f32_e32 v83, 0x37800000, v82
	v_cndmask_b32_e32 v82, v82, v83, vcc
	v_cmp_class_f32_e32 vcc, v80, v230
	s_nop 1
	v_cndmask_b32_e32 v80, v82, v80, vcc
	v_div_scale_f32 v82, s[26:27], v80, v80, 1.0
	v_rcp_f32_e32 v83, v82
	s_nop 0
	v_fma_f32 v158, -v82, v83, 1.0
	v_fmac_f32_e32 v83, v158, v83
	v_div_scale_f32 v158, vcc, 1.0, v80, 1.0
	v_mul_f32_e32 v159, v158, v83
	v_fma_f32 v160, -v82, v159, v158
	v_fmac_f32_e32 v159, v160, v83
	v_fma_f32 v82, -v82, v159, v158
	v_div_fmas_f32 v82, v82, v83, v159
	v_div_fixup_f32 v80, v82, v80, 1.0
	v_pk_mul_f32 v[82:83], v[136:137], v[80:81] op_sel_hi:[1,0]
	v_pk_mul_f32 v[136:137], v[138:139], v[80:81] op_sel_hi:[1,0]
	s_nop 0
	v_pk_mul_f32 v[138:139], v[118:119], v[136:137]
	v_pk_mul_f32 v[136:137], v[116:117], v[82:83]
	v_pk_mul_f32 v[82:83], v[144:145], v[80:81] op_sel_hi:[1,0]
	v_pk_mul_f32 v[116:117], v[146:147], v[80:81] op_sel_hi:[1,0]
	v_pk_mul_f32 v[144:145], v[120:121], v[82:83]
	v_pk_mul_f32 v[146:147], v[122:123], v[116:117]
	v_pk_mul_f32 v[82:83], v[132:133], v[80:81] op_sel_hi:[1,0]
	v_pk_mul_f32 v[116:117], v[134:135], v[80:81] op_sel_hi:[1,0]
	v_pk_mul_f32 v[132:133], v[128:129], v[82:83]
	v_pk_mul_f32 v[134:135], v[130:131], v[116:117]
	v_pk_mul_f32 v[82:83], v[140:141], v[80:81] op_sel_hi:[1,0]
	v_pk_mul_f32 v[116:117], v[142:143], v[80:81] op_sel_hi:[1,0]
	v_pk_mul_f32 v[140:141], v[124:125], v[82:83]
	v_pk_mul_f32 v[142:143], v[126:127], v[116:117]
	s_cmpk_lg_i32 s7, 0xc78f
	s_cbranch_scc1 .LBB0_3470
